# loop-edge: P5 tile loop back edge rotated (one branch per tile instead of two); xattn tile-3 row sum as packed add tree
# speedup vs baseline: 1.0026x; 1.0026x over previous
;     ...
;         for (int ks = 0; ks < DQK / 32; ++ks)
; #pragma unroll
;             for (int ni = 0; ni < 4; ++ni) { const bf16x8 kf = *(const bf16x8*)(cK + (ni * 16 + fr) * LDK + ks * 32 + fq * 8);
; #pragma unroll
;                 for (int mi = 0; mi < MIA; ++mi) s[mi][ni] = __builtin_amdgcn_mfma_f32_16x16x32_bf16(kf, qf[mi][ks], s[mi][ni], 0, 0, 0); }
;         }
;         __syncthreads();
;         slot = nslot;
;         if (live) {
;         bf16x8 pf[MIA][2];
; #pragma unroll
;         for (int mi = 0; mi < MIA; ++mi) {
;             float mx = -1e30f;
;             if (CAUSAL && kt * 64 + 63 > q0 + w * 16 * MIA) {
;                 const int qabs = q0 + w * 16 * MIA + mi * 16 + fr;
; #pragma unroll
;                 for (int ni = 0; ni < 4; ++ni)
; #pragma unroll
;                     for (int r = 0; r < 4; ++r) { const int kabs = kt * 64 + ni * 16 + fq * 4 + r; if (kabs > qabs) s[mi][ni][r] = -1e30f; }
;             }
; #pragma unroll
;             for (int ni = 0; ni < 4; ++ni) mx = fmaxf(mx, fmaxf(fmaxf(s[mi][ni][0], s[mi][ni][1]), fmaxf(s[mi][ni][2], s[mi][ni][3])));
;             mx = fmaxf(mx, __shfl_xor(mx, 16)); mx = fmaxf(mx, __shfl_xor(mx, 32));
;             const float mnew = fmaxf(mrun[mi], mx);
;             const float mc = mnew * scale_log2;
;             float ps = 0.f;
; #pragma unroll
;             for (int ni = 0; ni < 4; ++ni)
; #pragma unroll
;                 for (int r = 0; r < 4; ++r) { const float pv = __builtin_amdgcn_exp2f(__builtin_fmaf(s[mi][ni][r], scale_log2, -mc)); s[mi][ni][r] = pv; ps += pv; }
;             if (__builtin_amdgcn_ballot_w64(mnew > mrun[mi]) != 0ull) {
;                 const float alpha = __builtin_amdgcn_exp2f((mrun[mi] - mnew) * scale_log2);
;                 lrun[mi] *= alpha;
; #pragma unroll
;                 for (int di = 0; di < DV / 16; ++di) o[mi][di] *= alpha;
;             }
;             mrun[mi] = mnew;
;             lrun[mi] += ps;
.LBB0_387:
	s_or_b64 exec, exec, s[0:1]
	s_waitcnt vmcnt(2)
	v_pk_add_f32 v[102:103], v[102:103], v[104:105]
	v_pk_add_f32 v[106:107], v[106:107], v[108:109]
	v_pk_add_f32 v[72:73], v[72:73], v[74:75]
	v_pk_add_f32 v[76:77], v[76:77], v[78:79]
	v_pk_add_f32 v[102:103], v[102:103], v[106:107]
	v_pk_add_f32 v[72:73], v[72:73], v[76:77]
	v_pk_add_f32 v[102:103], v[102:103], v[72:73]
	v_add_f32_e32 v16, v102, v103
	s_waitcnt vmcnt(1)
	ds_write_b128 v95, v[24:27] offset:18432
	s_waitcnt vmcnt(0)
	ds_write_b128 v96, v[28:31] offset:18432
	v_add_u32_e32 v28, 0x12000, v90
	v_add_f32_e32 v68, v16, v99
	ds_read_b128 v[16:19], v28
	ds_read_b128 v[20:23], v28 offset:4608
	v_add_u32_e32 v69, 0x12040, v90
	ds_read_b128 v[24:27], v28 offset:9216
	ds_read_b128 v[64:67], v69
	ds_read_b128 v[28:31], v28 offset:13824
	s_waitcnt lgkmcnt(4)
	v_mfma_f32_16x16x32_bf16 v[16:19], v[16:19], v[12:15], 0
	s_waitcnt lgkmcnt(1)
	v_mfma_f32_16x16x32_bf16 v[16:19], v[64:67], v[8:11], v[16:19]
	ds_read_b128 v[64:67], v69 offset:4608
	v_mfma_f32_16x16x32_bf16 v[20:23], v[20:23], v[12:15], 0
	s_waitcnt lgkmcnt(0)
	v_mfma_f32_16x16x32_bf16 v[20:23], v[64:67], v[8:11], v[20:23]
	ds_read_b128 v[64:67], v69 offset:9216
	v_mfma_f32_16x16x32_bf16 v[24:27], v[24:27], v[12:15], 0
	s_waitcnt lgkmcnt(0)
	v_mfma_f32_16x16x32_bf16 v[24:27], v[64:67], v[8:11], v[24:27]
	ds_read_b128 v[64:67], v69 offset:13824
	v_add_u32_e32 v69, 0x12080, v90
	v_mfma_f32_16x16x32_bf16 v[28:31], v[28:31], v[12:15], 0
	s_waitcnt lgkmcnt(0)
	v_mfma_f32_16x16x32_bf16 v[28:31], v[64:67], v[8:11], v[28:31]
	ds_read_b128 v[64:67], v69
	s_waitcnt lgkmcnt(0)
	v_mfma_f32_16x16x32_bf16 v[16:19], v[64:67], v[4:7], v[16:19]
	ds_read_b128 v[64:67], v69 offset:4608
	s_waitcnt lgkmcnt(0)
	v_mfma_f32_16x16x32_bf16 v[64:67], v[64:67], v[4:7], v[20:23]
	s_nop 2
	ds_read_b128 v[20:23], v69 offset:9216
	s_waitcnt lgkmcnt(0)
	v_mfma_f32_16x16x32_bf16 v[24:27], v[20:23], v[4:7], v[24:27]
	ds_read_b128 v[20:23], v69 offset:13824
	v_add_u32_e32 v69, 0x120c0, v90
	s_waitcnt lgkmcnt(0)
	v_mfma_f32_16x16x32_bf16 v[70:73], v[20:23], v[4:7], v[28:31]
	ds_read_b128 v[20:23], v69
	s_waitcnt lgkmcnt(0)
	v_mfma_f32_16x16x32_bf16 v[20:23], v[20:23], v[0:3], v[16:19]
	s_nop 2
	ds_read_b128 v[16:19], v69 offset:4608
	s_waitcnt lgkmcnt(0)
	v_mfma_f32_16x16x32_bf16 v[28:31], v[16:19], v[0:3], v[64:67]
	ds_read_b128 v[16:19], v69 offset:9216
	s_nop 1
	v_max_f32_e32 v64, v23, v23
	v_max_f32_e32 v65, v22, v22
	s_waitcnt lgkmcnt(0)
	v_mfma_f32_16x16x32_bf16 v[24:27], v[16:19], v[0:3], v[24:27]
	ds_read_b128 v[16:19], v69 offset:13824
	v_max_f32_e32 v64, v65, v64
	v_max_f32_e32 v65, v31, v31
	s_waitcnt lgkmcnt(0)
	v_mfma_f32_16x16x32_bf16 v[16:19], v[16:19], v[0:3], v[70:73]
	v_max_f32_e32 v66, v30, v30
	v_max_f32_e32 v65, v66, v65
	v_max3_f32 v64, v20, v21, v64
	v_max3_f32 v65, v28, v29, v65
	v_max3_f32 v64, v64, s17, v65
	v_max_f32_e32 v65, v27, v27
	v_max_f32_e32 v66, v26, v26
	v_max_f32_e32 v65, v66, v65
	v_max_f32_e32 v66, v19, v19
	v_max_f32_e32 v67, v18, v18
	v_max_f32_e32 v66, v67, v66
	v_max3_f32 v65, v24, v25, v65
	v_max3_f32 v66, v16, v17, v66
	v_max3_f32 v64, v64, v65, v66
	ds_bpermute_b32 v65, v82, v64
	s_waitcnt lgkmcnt(0)
	s_barrier
	v_max_f32_e32 v65, v65, v65
	v_max_f32_e32 v64, v64, v65
	ds_bpermute_b32 v65, v83, v64
	s_waitcnt lgkmcnt(0)
	v_max3_f32 v69, v101, v64, v65
	v_cmp_gt_f32_e32 vcc, v69, v101
	s_cbranch_vccz .LBB0_389
	v_sub_f32_e32 v64, v101, v69
	v_mul_f32_e32 v64, 0x3e0293ee, v64
	v_exp_f32_e32 v64, v64
	s_nop 0
	v_pk_mul_f32 v[38:39], v[38:39], v[64:65] op_sel_hi:[1,0]
	v_pk_mul_f32 v[36:37], v[36:37], v[64:65] op_sel_hi:[1,0]
	v_pk_mul_f32 v[50:51], v[50:51], v[64:65] op_sel_hi:[1,0]
	v_pk_mul_f32 v[48:49], v[48:49], v[64:65] op_sel_hi:[1,0]
	v_pk_mul_f32 v[54:55], v[54:55], v[64:65] op_sel_hi:[1,0]
	v_pk_mul_f32 v[52:53], v[52:53], v[64:65] op_sel_hi:[1,0]
	v_pk_mul_f32 v[58:59], v[58:59], v[64:65] op_sel_hi:[1,0]
	v_pk_mul_f32 v[56:57], v[56:57], v[64:65] op_sel_hi:[1,0]
	v_pk_mul_f32 v[62:63], v[62:63], v[64:65] op_sel_hi:[1,0]
	v_pk_mul_f32 v[60:61], v[60:61], v[64:65] op_sel_hi:[1,0]
	v_pk_mul_f32 v[46:47], v[46:47], v[64:65] op_sel_hi:[1,0]
	v_pk_mul_f32 v[44:45], v[44:45], v[64:65] op_sel_hi:[1,0]
	v_pk_mul_f32 v[42:43], v[42:43], v[64:65] op_sel_hi:[1,0]
	v_pk_mul_f32 v[40:41], v[40:41], v[64:65] op_sel_hi:[1,0]
	v_pk_mul_f32 v[34:35], v[34:35], v[64:65] op_sel_hi:[1,0]
	v_pk_mul_f32 v[32:33], v[32:33], v[64:65] op_sel_hi:[1,0]
	v_mul_f32_e32 v68, v68, v64

;     ...
;     for (int kt = 0; kt < nkt; ++kt) {
;         const int nslot = slot == 2 ? 0 : slot + 1;
;     ...
;         slot = nslot;
.LBB0_718:
	s_or_b64 exec, exec, s[2:3]
	s_add_i32 s56, s56, 1
	s_add_i32 s29, s29, 64
	s_mov_b32 s2, s57
	s_cmp_lg_u32 s28, s56
	s_cbranch_scc1 .LBB0_696
